# stack20: stack18 + P4 cmp top-k threshold search counts with batched compares + carry-in adds (no wait-state nops, no cndmask)
# speedup vs baseline: 1.0093x; 1.0093x over previous
.LBB0_1398:
	v_lshlrev_b32_e64 v20, v19, 1
	v_or_b32_e32 v20, v20, v18
	v_mov_b32_e32 v21, 0
	v_cmp_ge_u32_e64 s[0:1], v2, v20
	v_cmp_ge_u32_e64 s[98:99], v3, v20
	v_cmp_ge_u32_e64 s[100:101], v4, v20
	v_cmp_ge_u32_e32 vcc, v5, v20
	v_addc_co_u32_e64 v21, s[0:1], 0, v21, s[0:1]
	v_addc_co_u32_e64 v21, s[98:99], 0, v21, s[98:99]
	v_addc_co_u32_e64 v21, s[100:101], 0, v21, s[100:101]
	v_addc_co_u32_e32 v21, vcc, 0, v21, vcc
	v_cmp_ge_u32_e64 s[0:1], v6, v20
	v_cmp_ge_u32_e64 s[98:99], v7, v20
	v_cmp_ge_u32_e64 s[100:101], v8, v20
	v_cmp_ge_u32_e32 vcc, v9, v20
	v_addc_co_u32_e64 v21, s[0:1], 0, v21, s[0:1]
	v_addc_co_u32_e64 v21, s[98:99], 0, v21, s[98:99]
	v_addc_co_u32_e64 v21, s[100:101], 0, v21, s[100:101]
	v_addc_co_u32_e32 v21, vcc, 0, v21, vcc
	v_cmp_ge_u32_e64 s[0:1], v10, v20
	v_cmp_ge_u32_e64 s[98:99], v11, v20
	v_cmp_ge_u32_e64 s[100:101], v12, v20
	v_cmp_ge_u32_e32 vcc, v13, v20
	v_addc_co_u32_e64 v21, s[0:1], 0, v21, s[0:1]
	v_addc_co_u32_e64 v21, s[98:99], 0, v21, s[98:99]
	v_addc_co_u32_e64 v21, s[100:101], 0, v21, s[100:101]
	v_addc_co_u32_e32 v21, vcc, 0, v21, vcc
	v_cmp_ge_u32_e64 s[0:1], v14, v20
	v_cmp_ge_u32_e64 s[98:99], v15, v20
	v_cmp_ge_u32_e64 s[100:101], v16, v20
	v_cmp_ge_u32_e32 vcc, v17, v20
	v_addc_co_u32_e64 v21, s[0:1], 0, v21, s[0:1]
	v_addc_co_u32_e64 v21, s[98:99], 0, v21, s[98:99]
	v_addc_co_u32_e64 v21, s[100:101], 0, v21, s[100:101]
	v_addc_co_u32_e32 v21, vcc, 0, v21, vcc
	s_nop 1
	v_add_u32_dpp v21, v21, v21 quad_perm:[1,0,3,2] row_mask:0xf bank_mask:0xf bound_ctrl:1
	s_nop 1
	v_add_u32_dpp v21, v21, v21 quad_perm:[2,3,0,1] row_mask:0xf bank_mask:0xf bound_ctrl:1
	s_nop 1
	v_add_u32_dpp v21, v21, v21 row_half_mirror row_mask:0xf bank_mask:0xf bound_ctrl:1
	v_cmp_eq_u32_e64 s[0:1], 13, v21
	v_cmp_gt_i32_e32 vcc, 13, v21
	s_or_b64 s[0:1], s[2:3], s[0:1]
	s_or_b64 vcc, s[2:3], vcc
	s_xor_b64 s[2:3], s[0:1], -1
	v_cndmask_b32_e32 v18, v20, v18, vcc
	v_cndmask_b32_e64 v20, 0, 1, s[2:3]
	v_cmp_ne_u32_e32 vcc, 0, v20
	s_cmp_eq_u64 vcc, 0
	s_cselect_b64 s[2:3], -1, 0
	v_subrev_co_u32_e32 v19, vcc, 1, v19
	s_or_b64 s[2:3], s[2:3], vcc
	s_andn2_b64 vcc, exec, s[2:3]
	s_mov_b64 s[2:3], s[0:1]
	s_cbranch_vccnz .LBB0_1398

	.amdhsa_kernel _Z10fwd_kernel4Args
		.amdhsa_group_segment_fixed_size 0
		.amdhsa_private_segment_fixed_size 0
		.amdhsa_kernarg_size 544
		.amdhsa_user_sgpr_count 2
		.amdhsa_user_sgpr_dispatch_ptr 0
		.amdhsa_user_sgpr_queue_ptr 0
		.amdhsa_user_sgpr_kernarg_segment_ptr 1
		.amdhsa_user_sgpr_dispatch_id 0
		.amdhsa_user_sgpr_kernarg_preload_length 0
		.amdhsa_user_sgpr_kernarg_preload_offset 0
		.amdhsa_user_sgpr_private_segment_size 0
		.amdhsa_uses_dynamic_stack 0
		.amdhsa_enable_private_segment 0
		.amdhsa_system_sgpr_workgroup_id_x 1
		.amdhsa_system_sgpr_workgroup_id_y 0
		.amdhsa_system_sgpr_workgroup_id_z 0
		.amdhsa_system_sgpr_workgroup_info 0
		.amdhsa_system_vgpr_workitem_id 0
		.amdhsa_next_free_vgpr 249
		.amdhsa_next_free_sgpr 102
		.amdhsa_accum_offset 252
		.amdhsa_reserve_vcc 1
		.amdhsa_float_round_mode_32 0
		.amdhsa_float_round_mode_16_64 0
		.amdhsa_float_denorm_mode_32 3
		.amdhsa_float_denorm_mode_16_64 3
		.amdhsa_dx10_clamp 1
		.amdhsa_ieee_mode 1
		.amdhsa_fp16_overflow 0
		.amdhsa_tg_split 0
		.amdhsa_exception_fp_ieee_invalid_op 0
		.amdhsa_exception_fp_denorm_src 0
		.amdhsa_exception_fp_ieee_div_zero 0
		.amdhsa_exception_fp_ieee_overflow 0
		.amdhsa_exception_fp_ieee_underflow 0
		.amdhsa_exception_fp_ieee_inexact 0
		.amdhsa_exception_int_div_zero 0
	.end_amdhsa_kernel

amdhsa.kernels:
  - .agpr_count:     0
    .args:
      - .offset:         0
        .size:           288
        .value_kind:     by_value
      - .offset:         288
        .size:           4
        .value_kind:     hidden_block_count_x
      - .offset:         292
        .size:           4
        .value_kind:     hidden_block_count_y
      - .offset:         296
        .size:           4
        .value_kind:     hidden_block_count_z
      - .offset:         300
        .size:           2
        .value_kind:     hidden_group_size_x
      - .offset:         302
        .size:           2
        .value_kind:     hidden_group_size_y
      - .offset:         304
        .size:           2
        .value_kind:     hidden_group_size_z
      - .offset:         306
        .size:           2
        .value_kind:     hidden_remainder_x
      - .offset:         308
        .size:           2
        .value_kind:     hidden_remainder_y
      - .offset:         310
        .size:           2
        .value_kind:     hidden_remainder_z
      - .offset:         328
        .size:           8
        .value_kind:     hidden_global_offset_x
      - .offset:         336
        .size:           8
        .value_kind:     hidden_global_offset_y
      - .offset:         344
        .size:           8
        .value_kind:     hidden_global_offset_z
      - .offset:         352
        .size:           2
        .value_kind:     hidden_grid_dims
      - .offset:         408
        .size:           4
        .value_kind:     hidden_dynamic_lds_size
    .group_segment_fixed_size: 0
    .kernarg_segment_align: 8
    .kernarg_segment_size: 544
    .language:       OpenCL C
    .language_version:
      - 2
      - 0
    .max_flat_workgroup_size: 512
    .name:           _Z10fwd_kernel4Args
    .private_segment_fixed_size: 0
    .sgpr_count:     108
    .sgpr_spill_count: 337
    .symbol:         _Z10fwd_kernel4Args.kd
    .uniform_work_group_size: 1
    .uses_dynamic_stack: false
    .vgpr_count:     249
    .vgpr_spill_count: 0
    .wavefront_size: 64
